# v102 + fc2 epilogue residual x-tile staged through LDS (EPI_XLDS)
# baseline (speedup 1.0000x reference)
.LBB0_542:
	v_readlane_b32 s30, v248, 33
	v_readlane_b32 s31, v248, 34
	v_readfirstlane_b32 s29, v63
	s_lshl_b32 s34, s8, 12
	s_lshl_b32 s35, s10, 2
	s_add_u32 s34, s34, s35
	s_add_u32 s30, s30, s34
	s_addc_u32 s31, s31, 0
	v_lshrrev_b32_e32 v150, 5, v167
	v_and_b32_e32 v151, 31, v167
	v_xor_b32_e32 v165, v151, v150
	v_lshlrev_b32_e32 v165, 4, v165
	v_lshl_add_u32 v166, v150, 12, v165
	v_xor_b32_e32 v168, 0x80, v166
	s_add_u32 m0, s29, 0x0
	s_add_u32 s34, s30, 0x0
	s_addc_u32 s35, s31, 0
	global_load_lds_dwordx4 v166, s[34:35]
	s_add_u32 m0, s29, 0x1000
	s_add_u32 s34, s30, 0x8000
	s_addc_u32 s35, s31, 0
	global_load_lds_dwordx4 v168, s[34:35]
	s_add_u32 m0, s29, 0x2000
	s_add_u32 s34, s30, 0x10000
	s_addc_u32 s35, s31, 0
	global_load_lds_dwordx4 v166, s[34:35]
	s_add_u32 m0, s29, 0x3000
	s_add_u32 s34, s30, 0x18000
	s_addc_u32 s35, s31, 0
	global_load_lds_dwordx4 v168, s[34:35]
	s_add_u32 m0, s29, 0x4000
	s_add_u32 s34, s30, 0x20000
	s_addc_u32 s35, s31, 0
	global_load_lds_dwordx4 v166, s[34:35]
	s_add_u32 m0, s29, 0x5000
	s_add_u32 s34, s30, 0x28000
	s_addc_u32 s35, s31, 0
	global_load_lds_dwordx4 v168, s[34:35]
	s_add_u32 m0, s29, 0x6000
	s_add_u32 s34, s30, 0x30000
	s_addc_u32 s35, s31, 0
	global_load_lds_dwordx4 v166, s[34:35]
	s_add_u32 m0, s29, 0x7000
	s_add_u32 s34, s30, 0x38000
	s_addc_u32 s35, s31, 0
	global_load_lds_dwordx4 v168, s[34:35]
	s_add_u32 m0, s29, 0x10000
	s_add_u32 s34, s30, 0x40000
	s_addc_u32 s35, s31, 0
	global_load_lds_dwordx4 v166, s[34:35]
	s_add_u32 m0, s29, 0x11000
	s_add_u32 s34, s30, 0x48000
	s_addc_u32 s35, s31, 0
	global_load_lds_dwordx4 v168, s[34:35]
	s_add_u32 m0, s29, 0x12000
	s_add_u32 s34, s30, 0x50000
	s_addc_u32 s35, s31, 0
	global_load_lds_dwordx4 v166, s[34:35]
	s_add_u32 m0, s29, 0x13000
	s_add_u32 s34, s30, 0x58000
	s_addc_u32 s35, s31, 0
	global_load_lds_dwordx4 v168, s[34:35]
	ds_read_b128 v[58:61], v72 offset:32768
	ds_read_b128 v[76:79], v72 offset:34816
	ds_read_b128 v[80:83], v72 offset:36864
	ds_read_b128 v[84:87], v73 offset:49152
	ds_read_b128 v[88:91], v73 offset:51200
	ds_read_b128 v[92:95], v73 offset:53248
	ds_read_b128 v[96:99], v73 offset:55296
	s_waitcnt lgkmcnt(0)
	v_mfma_f32_16x16x32_bf16 v[44:47], v[84:87], v[58:61], v[44:47]
	v_mfma_f32_16x16x32_bf16 v[28:31], v[84:87], v[76:79], v[28:31]
	v_mfma_f32_16x16x32_bf16 v[12:15], v[84:87], v[80:83], v[12:15]
	v_mfma_f32_16x16x32_bf16 v[40:43], v[88:91], v[58:61], v[40:43]
	v_mfma_f32_16x16x32_bf16 v[36:39], v[92:95], v[58:61], v[36:39]
	v_mfma_f32_16x16x32_bf16 v[32:35], v[96:99], v[58:61], v[32:35]
	v_mfma_f32_16x16x32_bf16 v[24:27], v[88:91], v[76:79], v[24:27]
	v_mfma_f32_16x16x32_bf16 v[20:23], v[92:95], v[76:79], v[20:23]
	v_mfma_f32_16x16x32_bf16 v[16:19], v[96:99], v[76:79], v[16:19]
	v_mfma_f32_16x16x32_bf16 v[8:11], v[88:91], v[80:83], v[8:11]
	v_mfma_f32_16x16x32_bf16 v[4:7], v[92:95], v[80:83], v[4:7]
	v_mfma_f32_16x16x32_bf16 v[0:3], v[96:99], v[80:83], v[0:3]
	ds_read_b128 v[58:61], v74 offset:32768
	ds_read_b128 v[76:79], v74 offset:34816
	ds_read_b128 v[80:83], v74 offset:36864
	ds_read_b128 v[84:87], v75 offset:49152
	ds_read_b128 v[88:91], v75 offset:51200
	ds_read_b128 v[92:95], v75 offset:53248
	ds_read_b128 v[96:99], v75 offset:55296
	s_waitcnt lgkmcnt(0)
	v_mfma_f32_16x16x32_bf16 v[44:47], v[84:87], v[58:61], v[44:47]
	v_mfma_f32_16x16x32_bf16 v[28:31], v[84:87], v[76:79], v[28:31]
	v_mfma_f32_16x16x32_bf16 v[12:15], v[84:87], v[80:83], v[12:15]
	v_mfma_f32_16x16x32_bf16 v[100:103], v[88:91], v[58:61], v[40:43]
	v_mfma_f32_16x16x32_bf16 v[8:11], v[88:91], v[80:83], v[8:11]
	v_mfma_f32_16x16x32_bf16 v[4:7], v[92:95], v[80:83], v[4:7]
	v_mfma_f32_16x16x32_bf16 v[0:3], v[96:99], v[80:83], v[0:3]
	v_mfma_f32_16x16x32_bf16 v[36:39], v[92:95], v[58:61], v[36:39]
	v_mfma_f32_16x16x32_bf16 v[32:35], v[96:99], v[58:61], v[32:35]
	v_mfma_f32_16x16x32_bf16 v[24:27], v[88:91], v[76:79], v[24:27]
	v_mfma_f32_16x16x32_bf16 v[20:23], v[92:95], v[76:79], v[20:23]
	v_mfma_f32_16x16x32_bf16 v[16:19], v[96:99], v[76:79], v[16:19]
	v_add_u32_e32 v160, s8, v64
	v_or_b32_e32 v160, v160, v62
	v_or_b32_e32 v161, s10, v69
	v_lshlrev_b32_e32 v161, 2, v161
	v_lshl_add_u32 v162, v160, 12, v161
	v_add_u32_e32 v163, 0x10000, v162
	v_add_u32_e32 v164, 0x20000, v162
	v_readfirstlane_b32 s1, v160
	v_readlane_b32 s42, v248, 33
	v_readlane_b32 s43, v248, 34
	v_lshrrev_b32_e32 v165, 2, v69
	v_xor_b32_e32 v165, v165, v62
	v_lshlrev_b32_e32 v165, 4, v165
	v_lshl_add_u32 v165, v62, 9, v165
	v_cmp_ne_u32_e32 vcc, 0, v64
	v_mov_b32_e32 v150, 0x6000
	v_mov_b32_e32 v151, 0xe000
	v_cndmask_b32_e32 v166, 0, v150, vcc
	v_cndmask_b32_e32 v151, 0, v151, vcc
	v_add_u32_e32 v168, 0x2000, v151
	v_add_u32_e32 v169, 0x4000, v151
	s_waitcnt vmcnt(0)
	s_barrier
	v_xor_b32_e32 v170, 0, v165
	v_add_u32_e32 v170, v170, v166
	ds_read_b128 v[110:113], v170
	v_xor_b32_e32 v170, 64, v165
	v_add_u32_e32 v170, v170, v166
	ds_read_b128 v[114:117], v170
	v_xor_b32_e32 v170, 128, v165
	v_add_u32_e32 v170, v170, v166
	ds_read_b128 v[118:121], v170
	v_xor_b32_e32 v170, 192, v165
	v_add_u32_e32 v170, v170, v166
	ds_read_b128 v[122:125], v170
	v_xor_b32_e32 v170, 0, v165
	v_add_u32_e32 v170, v170, v168
	ds_read_b128 v[126:129], v170
	v_xor_b32_e32 v170, 64, v165
	v_add_u32_e32 v170, v170, v168
	ds_read_b128 v[130:133], v170
	v_xor_b32_e32 v170, 128, v165
	v_add_u32_e32 v170, v170, v168
	ds_read_b128 v[134:137], v170
	v_xor_b32_e32 v170, 192, v165
	v_add_u32_e32 v170, v170, v168
	ds_read_b128 v[138:141], v170
	v_xor_b32_e32 v170, 0, v165
	v_add_u32_e32 v170, v170, v169
	ds_read_b128 v[142:145], v170
	v_xor_b32_e32 v170, 64, v165
	v_add_u32_e32 v170, v170, v169
	ds_read_b128 v[146:149], v170
	v_xor_b32_e32 v170, 128, v165
	v_add_u32_e32 v170, v170, v169
	ds_read_b128 v[212:215], v170
	v_xor_b32_e32 v170, 192, v165
	v_add_u32_e32 v170, v170, v169
	ds_read_b128 v[216:219], v170
	s_add_i32 s0, s1, 0xfffff000
	s_lshr_b32 s0, s0, 10
	s_add_i32 s0, s0, 1
	s_cmp_lt_u32 s1, 0x1000
	s_cselect_b32 s0, 0, s0
	s_add_i32 s0, s0, s17
	s_mul_i32 s0, s0, 0x6000
	s_add_u32 s36, s24, s0
	s_addc_u32 s37, s25, 0
	s_add_u32 s36, s36, 0x15000
	s_addc_u32 s37, s37, 0
	global_load_dwordx4 v[76:79], v161, s[36:37]
	global_load_dwordx4 v[80:83], v161, s[36:37] offset:64
	global_load_dwordx4 v[84:87], v161, s[36:37] offset:128
	global_load_dwordx4 v[88:91], v161, s[36:37] offset:192
	s_add_i32 s1, s1, 16
	s_add_i32 s0, s1, 0xfffff000
	s_lshr_b32 s0, s0, 10
	s_add_i32 s0, s0, 1
	s_cmp_lt_u32 s1, 0x1000
	s_cselect_b32 s0, 0, s0
	s_add_i32 s0, s0, s17
	s_mul_i32 s0, s0, 0x6000
	s_add_u32 s36, s24, s0
	s_addc_u32 s37, s25, 0
	s_add_u32 s36, s36, 0x15000
	s_addc_u32 s37, s37, 0
	global_load_dwordx4 v[92:95], v161, s[36:37]
	global_load_dwordx4 v[96:99], v161, s[36:37] offset:64
	global_load_dwordx4 v[220:223], v161, s[36:37] offset:128
	global_load_dwordx4 v[174:177], v161, s[36:37] offset:192
	s_add_i32 s1, s1, 16
	s_add_i32 s0, s1, 0xfffff000
	s_lshr_b32 s0, s0, 10
	s_add_i32 s0, s0, 1
	s_cmp_lt_u32 s1, 0x1000
	s_cselect_b32 s0, 0, s0
	s_add_i32 s0, s0, s17
	s_mul_i32 s0, s0, 0x6000
	s_add_u32 s36, s24, s0
	s_addc_u32 s37, s25, 0
	s_add_u32 s36, s36, 0x15000
	s_addc_u32 s37, s37, 0
	global_load_dwordx4 v[178:181], v161, s[36:37]
	global_load_dwordx4 v[234:237], v161, s[36:37] offset:64
	global_load_dwordx4 v[238:241], v161, s[36:37] offset:128
	global_load_dwordx4 v[242:245], v161, s[36:37] offset:192
	s_waitcnt vmcnt(8) lgkmcnt(8)
	v_pk_fma_f32 v[110:111], v[44:45], v[76:77], v[110:111]
	v_pk_fma_f32 v[112:113], v[46:47], v[78:79], v[112:113]
	v_pk_fma_f32 v[114:115], v[100:101], v[80:81], v[114:115]
	v_pk_fma_f32 v[116:117], v[102:103], v[82:83], v[116:117]
	v_pk_fma_f32 v[118:119], v[36:37], v[84:85], v[118:119]
	v_pk_fma_f32 v[120:121], v[38:39], v[86:87], v[120:121]
	v_pk_fma_f32 v[122:123], v[32:33], v[88:89], v[122:123]
	v_pk_fma_f32 v[124:125], v[34:35], v[90:91], v[124:125]
	global_store_dwordx4 v162, v[110:113], s[42:43] nt
	global_store_dwordx4 v162, v[114:117], s[42:43] offset:64 nt
	global_store_dwordx4 v162, v[118:121], s[42:43] offset:128 nt
	global_store_dwordx4 v162, v[122:125], s[42:43] offset:192 nt
	s_waitcnt vmcnt(8) lgkmcnt(4)
	v_pk_fma_f32 v[126:127], v[28:29], v[92:93], v[126:127]
	v_pk_fma_f32 v[128:129], v[30:31], v[94:95], v[128:129]
	v_pk_fma_f32 v[130:131], v[24:25], v[96:97], v[130:131]
	v_pk_fma_f32 v[132:133], v[26:27], v[98:99], v[132:133]
	v_pk_fma_f32 v[134:135], v[20:21], v[220:221], v[134:135]
	v_pk_fma_f32 v[136:137], v[22:23], v[222:223], v[136:137]
	v_pk_fma_f32 v[138:139], v[16:17], v[174:175], v[138:139]
	v_pk_fma_f32 v[140:141], v[18:19], v[176:177], v[140:141]
	global_store_dwordx4 v163, v[126:129], s[42:43] nt
	global_store_dwordx4 v163, v[130:133], s[42:43] offset:64 nt
	global_store_dwordx4 v163, v[134:137], s[42:43] offset:128 nt
	global_store_dwordx4 v163, v[138:141], s[42:43] offset:192 nt
	s_waitcnt vmcnt(8) lgkmcnt(0)
	v_pk_fma_f32 v[142:143], v[12:13], v[178:179], v[142:143]
	v_pk_fma_f32 v[144:145], v[14:15], v[180:181], v[144:145]
	v_pk_fma_f32 v[146:147], v[8:9], v[234:235], v[146:147]
	v_pk_fma_f32 v[148:149], v[10:11], v[236:237], v[148:149]
	v_pk_fma_f32 v[212:213], v[4:5], v[238:239], v[212:213]
	v_pk_fma_f32 v[214:215], v[6:7], v[240:241], v[214:215]
	v_pk_fma_f32 v[216:217], v[0:1], v[242:243], v[216:217]
	v_pk_fma_f32 v[218:219], v[2:3], v[244:245], v[218:219]
	global_store_dwordx4 v164, v[142:145], s[42:43] nt
	global_store_dwordx4 v164, v[146:149], s[42:43] offset:64 nt
	global_store_dwordx4 v164, v[212:215], s[42:43] offset:128 nt
	global_store_dwordx4 v164, v[216:219], s[42:43] offset:192 nt
	s_movk_i32 s1, 0xfff
	s_movk_i32 s0, 0x1800
	v_readlane_b32 s36, v248, 27
	v_readlane_b32 s37, v248, 28
	v_readlane_b32 s38, v248, 29
	v_readlane_b32 s39, v248, 30
	v_readlane_b32 s40, v248, 31
	v_readlane_b32 s41, v248, 32
	v_readlane_b32 s42, v248, 33
	v_readlane_b32 s43, v248, 34
	s_cmp_eq_u32 s18, s16
	s_mov_b64 s[8:9], s[2:3]
	s_cbranch_scc1 .LBB0_563
